# retention chunk top: role vmcnt wait + 18 register copies moved before the B1 wait/barrier (overlap LDS write latency), on v51
# speedup vs baseline: 1.0144x; 1.0144x over previous
; #define LAS __attribute__((address_space(3)))
; __device__ __forceinline__ void ret_mfma(const Params& P, LAS unsigned char* lds, int wave) {
;     ...
; #pragma unroll
;             for (int i = 0; i < 4; ++i) { const int id = t + 512 * i, r = id >> 5, ch = id & 31;
;                 *(LAS u32x4*)(lds + Q_OFF + r * QP + ch * 16) = pq[i]; *(LAS u32x4*)(lds + K_OFF + r * QP + ch * 16) = pkk[i]; }
;             *(LAS u32x4*)(lds + V_OFF + vr * VP + vc * 16) = pvv;
;             __syncthreads();
.LBB0_255:
	s_add_i32 s14, s29, 1
	s_cmp_lg_u32 s29, 63
	s_waitcnt lgkmcnt(0)
	ds_write_b128 v173, v[48:51]
	ds_write_b128 v173, v[52:55] offset:33792
	ds_write_b128 v174, v[56:59]
	ds_write_b128 v174, v[60:63] offset:33792
	ds_write_b128 v175, v[64:67]
	ds_write_b128 v175, v[68:71] offset:33792
	ds_write_b128 v176, v[72:75]
	ds_write_b128 v176, v[76:79] offset:33792
	ds_write_b128 v177, v[80:83]
	s_andn2_b64 vcc, exec, s[10:11]
	s_cbranch_vccnz .Lret_wait_lo
	s_waitcnt vmcnt(3)
	s_branch .Lret_wait_done

; __device__ __forceinline__ void ret_mfma(const Params& P, LAS unsigned char* lds, int wave) {
;     ...
;             __syncthreads();
;             if (c + 1 < 64) { const size_t r1 = rb + (size_t)(c + 1) * 64;
; #pragma unroll
;                 for (int i = 0; i < 4; ++i) { const int id = t + 512 * i, r = id >> 5, ch = id & 31;
;                     pq[i] = *(const u32x4*)(QK + (r1 + r) * 2048 + hh * 256 + ch * 8); pkk[i] = *(const u32x4*)(QK + (r1 + r) * 2048 + 1024 + hh * 256 + ch * 8); }
;                 pvv = *(const u32x4*)(V + (r1 + vr) * 2048 + hh * 512 + slice * 64 + vc * 8); }
.Lret_wait_done:
	v_mov_b64_e32 v[48:49], v[226:227]
	v_mov_b64_e32 v[50:51], v[228:229]
	v_mov_b64_e32 v[52:53], v[230:231]
	v_mov_b64_e32 v[54:55], v[232:233]
	v_mov_b64_e32 v[56:57], v[234:235]
	v_mov_b64_e32 v[58:59], v[236:237]
	v_mov_b64_e32 v[60:61], v[238:239]
	v_mov_b64_e32 v[62:63], v[240:241]
	v_mov_b64_e32 v[64:65], v[246:247]
	v_mov_b64_e32 v[66:67], v[248:249]
	v_mov_b64_e32 v[68:69], v[250:251]
	v_mov_b64_e32 v[70:71], v[252:253]
	v_mov_b64_e32 v[72:73], v[206:207]
	v_mov_b64_e32 v[74:75], v[208:209]
	v_mov_b64_e32 v[76:77], v[130:131]
	v_mov_b64_e32 v[78:79], v[132:133]
	v_mov_b64_e32 v[80:81], v[134:135]
	v_mov_b64_e32 v[82:83], v[136:137]
	s_waitcnt lgkmcnt(0)
	s_barrier
	s_cmp_lt_u32 s29, 62
	s_cbranch_scc0 .LBB0_257
	s_lshl_b32 s8, s14, 6
	s_add_i32 s8, s8, 64
	s_add_u32 s8, s18, s8
	s_addc_u32 s9, s19, 0
	s_lshl_b64 s[8:9], s[8:9], 12
	s_add_u32 s30, s8, s66
	s_addc_u32 s31, s9, s67
	s_add_u32 s34, s8, s62
	s_addc_u32 s35, s9, s63
	global_load_dwordx4 v[226:229], v138, s[30:31]
	global_load_dwordx4 v[230:233], v138, s[30:31] offset:2048
	global_load_dwordx4 v[234:237], v139, s[30:31]
	global_load_dwordx4 v[238:241], v139, s[30:31] offset:2048
	global_load_dwordx4 v[246:249], v140, s[30:31]
	global_load_dwordx4 v[250:253], v140, s[30:31] offset:2048
	global_load_dwordx4 v[206:209], v141, s[30:31]
	global_load_dwordx4 v[130:133], v141, s[30:31] offset:2048
	global_load_dwordx4 v[134:137], v185, s[34:35]
